# attention: second-half QK head K-fragment addresses computed before the barrier (on top of transpose-read hoist)
# speedup vs baseline: 1.0056x; 1.0011x over previous
; template <bool FIRST>
; __device__ __forceinline__ void partialSM(f32x16& p0, f32x16& p1, float& m_reg, float& mn, float& alpha) {
;     ...
;     for (int r = 0; r < 16; ++r) p0[r] = __builtin_amdgcn_exp2f(p0[r]);
; }
; __device__ __forceinline__ void finishSM(f32x16& p0, f32x16& p1, float alpha, float& l_reg, bf16x8& pa0, bf16x8& pa1, bf16x8& pa2, bf16x8& pa3) {
; #pragma unroll
;     for (int r = 0; r < 16; ++r) p1[r] = __builtin_amdgcn_exp2f(p1[r]);
; __device__ __forceinline__ void qkt(f32x16& p0, f32x16& p1, const char* Kn, const bf16x8* qr, int r32, int hi) {
;     const char* Kr = Kn + KR_OFF;
;     p0 = f32x16{}; p1 = f32x16{};
;     __builtin_amdgcn_s_setprio(1);
; #pragma unroll
;     for (int d0 = 0; d0 < 8; ++d0) { const int cb = (d0 * 16 + hi * 8) * 2;
;         const bf16x8 b0 = *reinterpret_cast<const bf16x8*>(Kn + KNSWZ(r32, cb));
;         const bf16x8 b1 = *reinterpret_cast<const bf16x8*>(Kn + KNSWZ(32 + r32, cb));
;         p0 = __builtin_amdgcn_mfma_f32_32x32x16_bf16(b0, qr[d0], p0, 0, 0, 0);
;         p1 = __builtin_amdgcn_mfma_f32_32x32x16_bf16(b1, qr[d0], p1, 0, 0, 0); }
; #pragma unroll
;     for (int d0 = 0; d0 < 4; ++d0) { const int cb = (d0 * 16 + hi * 8) * 2;
;         const bf16x8 b0 = *reinterpret_cast<const bf16x8*>(Kr + KRSWZ(r32, cb));
;         const bf16x8 b1 = *reinterpret_cast<const bf16x8*>(Kr + KRSWZ(32 + r32, cb));
;         p0 = __builtin_amdgcn_mfma_f32_32x32x16_bf16(b0, qr[8 + d0], p0, 0, 0, 0);
;         p1 = __builtin_amdgcn_mfma_f32_32x32x16_bf16(b1, qr[8 + d0], p1, 0, 0, 0); }
; }
.LBB0_221:
	v_exp_f32_e32 v182, v98
	v_exp_f32_e32 v172, v96
	v_exp_f32_e32 v173, v97
	v_exp_f32_e32 v195, v99
	v_exp_f32_e32 v196, v100
	v_exp_f32_e32 v197, v101
	v_exp_f32_e32 v198, v102
	v_exp_f32_e32 v199, v103
	v_exp_f32_e32 v200, v104
	v_exp_f32_e32 v234, v105
	v_exp_f32_e32 v235, v106
	v_exp_f32_e32 v236, v107
	v_exp_f32_e32 v237, v108
	v_exp_f32_e32 v238, v109
	v_exp_f32_e32 v239, v110
	v_exp_f32_e32 v240, v111
	v_add_u32_e32 v68, s14, v207
	v_add_u32_e32 v186, s14, v210
	s_mul_i32 s0, s10, 0x6000
	s_add_i32 s16, s0, 0
	s_add_i32 s17, s16, s6
	s_add_i32 s18, s16, s8
	s_waitcnt vmcnt(0) lgkmcnt(0)
	s_barrier
	s_add_i32 s15, s7, s15
	s_setprio 1
	ds_read_b128 v[64:67], v68
	ds_read_b128 v[68:71], v68 offset:8192
	ds_read_b128 v[168:171], v186
	ds_read_b128 v[186:189], v186 offset:8192
	s_waitcnt lgkmcnt(0)
	v_mfma_f32_32x32x16_bf16 v[96:111], v[64:67], v[156:159], 0
	v_mfma_f32_32x32x16_bf16 v[64:79], v[68:71], v[156:159], 0
	v_mfma_f32_32x32x16_bf16 v[96:111], v[168:171], v[152:155], v[96:111]
	v_mfma_f32_32x32x16_bf16 v[64:79], v[186:189], v[152:155], v[64:79]
	v_add_u32_e32 v186, s14, v218
	ds_read_b128 v[168:171], v186
	ds_read_b128 v[186:189], v186 offset:8192
	s_mov_b32 m0, s17
	s_add_u32 s100, s72, 0x26580000
	s_addc_u32 s101, s73, 0
	global_load_lds_dwordx4 v178, s[100:101]
	s_waitcnt lgkmcnt(0)
	v_mfma_f32_32x32x16_bf16 v[96:111], v[168:171], v[148:151], v[96:111]
	v_mfma_f32_32x32x16_bf16 v[64:79], v[186:189], v[148:151], v[64:79]
	v_add_u32_e32 v186, s14, v221
	ds_read_b128 v[168:171], v186
	ds_read_b128 v[186:189], v186 offset:8192
	s_waitcnt lgkmcnt(0)
	v_mfma_f32_32x32x16_bf16 v[96:111], v[168:171], v[144:147], v[96:111]
	v_mfma_f32_32x32x16_bf16 v[64:79], v[186:189], v[144:147], v[64:79]
	v_add_u32_e32 v186, s14, v222
	ds_read_b128 v[168:171], v186
	ds_read_b128 v[186:189], v186 offset:8192
	s_add_i32 m0, s17, 0x400
	s_nop 0
	global_load_lds_dwordx4 v180, s[100:101]
	v_exp_f32_e32 v190, v88
	s_waitcnt lgkmcnt(0)
	v_mfma_f32_32x32x16_bf16 v[96:111], v[168:171], v[140:143], v[96:111]
	v_mfma_f32_32x32x16_bf16 v[64:79], v[186:189], v[140:143], v[64:79]
	v_add_u32_e32 v186, s14, v223
	ds_read_b128 v[168:171], v186
	ds_read_b128 v[186:189], v186 offset:8192
	v_exp_f32_e32 v191, v89
	s_waitcnt lgkmcnt(0)
	v_mfma_f32_32x32x16_bf16 v[96:111], v[168:171], v[136:139], v[96:111]
	v_mfma_f32_32x32x16_bf16 v[64:79], v[186:189], v[136:139], v[64:79]
	v_add_u32_e32 v186, s14, v224
	ds_read_b128 v[168:171], v186
	ds_read_b128 v[186:189], v186 offset:8192
	s_mov_b32 m0, s15
	s_add_u32 s100, s72, 0x26580100
	s_addc_u32 s101, s73, 0
	global_load_lds_dwordx4 v176, s[100:101]
	v_exp_f32_e32 v192, v90
	s_waitcnt lgkmcnt(0)
	v_mfma_f32_32x32x16_bf16 v[96:111], v[168:171], v[132:135], v[96:111]
	v_mfma_f32_32x32x16_bf16 v[64:79], v[186:189], v[132:135], v[64:79]
	v_add_u32_e32 v186, s14, v225
	ds_read_b128 v[168:171], v186
	ds_read_b128 v[186:189], v186 offset:8192
	v_exp_f32_e32 v193, v91
	s_waitcnt lgkmcnt(0)
	v_mfma_f32_32x32x16_bf16 v[96:111], v[168:171], v[128:131], v[96:111]
	v_mfma_f32_32x32x16_bf16 v[64:79], v[186:189], v[128:131], v[64:79]
	v_add_u32_e32 v186, s14, v226
	ds_read_b128 v[168:171], v186 offset:16384
	ds_read_b128 v[186:189], v186 offset:20480
	s_add_i32 m0, s15, 0x400
	s_add_u32 s100, s72, 0x26580180
	s_addc_u32 s101, s73, 0
	global_load_lds_dwordx4 v176, s[100:101]
	v_exp_f32_e32 v241, v92
	s_waitcnt lgkmcnt(0)
	v_mfma_f32_32x32x16_bf16 v[96:111], v[168:171], v[124:127], v[96:111]
	v_mfma_f32_32x32x16_bf16 v[64:79], v[186:189], v[124:127], v[64:79]
	v_add_u32_e32 v186, s14, v227
	ds_read_b128 v[168:171], v186 offset:16384
	ds_read_b128 v[186:189], v186 offset:20480
	v_exp_f32_e32 v242, v93
	s_waitcnt lgkmcnt(0)
	v_mfma_f32_32x32x16_bf16 v[96:111], v[168:171], v[120:123], v[96:111]
	v_mfma_f32_32x32x16_bf16 v[64:79], v[186:189], v[120:123], v[64:79]
	v_add_u32_e32 v186, s14, v228
	ds_read_b128 v[168:171], v186 offset:16384
	ds_read_b128 v[186:189], v186 offset:20480
	s_add_i32 m0, s18, 0x4000
	s_add_u32 s100, s72, 0x21206000
	s_addc_u32 s101, s73, 0
	global_load_lds_dwordx4 v174, s[100:101]
	v_exp_f32_e32 v94, v94
	s_waitcnt lgkmcnt(0)
	v_mfma_f32_32x32x16_bf16 v[96:111], v[168:171], v[116:119], v[96:111]
	v_mfma_f32_32x32x16_bf16 v[64:79], v[186:189], v[116:119], v[64:79]
	v_add_u32_e32 v186, s14, v229
	ds_read_b128 v[168:171], v186 offset:16384
	ds_read_b128 v[186:189], v186 offset:20480
	v_exp_f32_e32 v95, v95
	s_waitcnt lgkmcnt(0)
; __device__ __forceinline__ void finishSM(f32x16& p0, f32x16& p1, float alpha, float& l_reg, bf16x8& pa0, bf16x8& pa1, bf16x8& pa2, bf16x8& pa3) {
; #pragma unroll
;     for (int r = 0; r < 16; ++r) p1[r] = __builtin_amdgcn_exp2f(p1[r]);
;     float ps = 0;
; #pragma unroll
;     for (int r = 0; r < 16; ++r) ps += p0[r];
; #pragma unroll
;     for (int r = 0; r < 16; ++r) ps += p1[r];
;     { auto rr = __builtin_amdgcn_permlane32_swap(__float_as_uint(ps), __float_as_uint(ps), false, false);
;       ps = __uint_as_float(rr[0]) + __uint_as_float(rr[1]); }
;     l_reg = l_reg * alpha + ps;
;     ...
;     PK4(p0, 0, pa0); PK4(p0, 8, pa1); PK4(p1, 0, pa2); PK4(p1, 8, pa3);
;     ...
; }
; __device__ __forceinline__ void qkt(f32x16& p0, f32x16& p1, const char* Kn, const bf16x8* qr, int r32, int hi) {
;     const char* Kr = Kn + KR_OFF;
;     p0 = f32x16{}; p1 = f32x16{};
;     __builtin_amdgcn_s_setprio(1);
; #pragma unroll
;     for (int d0 = 0; d0 < 8; ++d0) { const int cb = (d0 * 16 + hi * 8) * 2;
;         const bf16x8 b0 = *reinterpret_cast<const bf16x8*>(Kn + KNSWZ(r32, cb));
;         const bf16x8 b1 = *reinterpret_cast<const bf16x8*>(Kn + KNSWZ(32 + r32, cb));
;         p0 = __builtin_amdgcn_mfma_f32_32x32x16_bf16(b0, qr[d0], p0, 0, 0, 0);
;         p1 = __builtin_amdgcn_mfma_f32_32x32x16_bf16(b1, qr[d0], p1, 0, 0, 0); }
; #pragma unroll
;     for (int d0 = 0; d0 < 4; ++d0) { const int cb = (d0 * 16 + hi * 8) * 2;
;         const bf16x8 b0 = *reinterpret_cast<const bf16x8*>(Kr + KRSWZ(r32, cb));
;         const bf16x8 b1 = *reinterpret_cast<const bf16x8*>(Kr + KRSWZ(32 + r32, cb));
;         p0 = __builtin_amdgcn_mfma_f32_32x32x16_bf16(b0, qr[8 + d0], p0, 0, 0, 0);
;         p1 = __builtin_amdgcn_mfma_f32_32x32x16_bf16(b1, qr[8 + d0], p1, 0, 0, 0); }
; }
; __device__ __forceinline__ int v_st(int k, int c) { const int kk = (k & ~0xC) | ((k & 4) << 1) | ((k & 8) >> 1); return ((kk >> 3) * 4 + (c >> 5)) * 512 + ((kk & 7) * 32 + (c & 31)) * 2; }
; __device__ __forceinline__ int v_rd_base(int lane) { return ((lane & 3) << 3) | (((lane >> 2) & 3) << 6) | (((lane >> 4) & 1) << 5) | (((lane >> 5) & 1) << 8); }
; template <int OFF> __device__ __forceinline__ s16x4 tr_read(int vb) {
;     s16x4 r; asm volatile("ds_read_b64_tr_b16 %0, %1 offset:%2" : "=&v"(r) : "v"(vb), "i"(OFF) : "memory"); return r;
; }
	v_mfma_f32_32x32x16_bf16 v[96:111], v[168:171], v[112:115], v[96:111]
	v_exp_f32_e32 v168, v80
	v_add_f32_e32 v80, 0, v172
	v_add_f32_e32 v80, v173, v80
	v_add_f32_e32 v80, v182, v80
	v_add_f32_e32 v80, v195, v80
	v_add_f32_e32 v80, v196, v80
	v_add_f32_e32 v80, v197, v80
	v_add_f32_e32 v80, v198, v80
	v_add_f32_e32 v80, v199, v80
	v_add_f32_e32 v80, v200, v80
	v_add_f32_e32 v80, v234, v80
	v_add_f32_e32 v80, v235, v80
	v_add_f32_e32 v80, v236, v80
	v_add_f32_e32 v80, v237, v80
	v_exp_f32_e32 v169, v81
	v_add_f32_e32 v80, v238, v80
	v_exp_f32_e32 v170, v82
	v_add_f32_e32 v80, v239, v80
	v_exp_f32_e32 v171, v83
	v_add_f32_e32 v80, v240, v80
	v_mfma_f32_32x32x16_bf16 v[64:79], v[186:189], v[112:115], v[64:79]
	v_exp_f32_e32 v186, v84
	v_add_f32_e32 v80, v168, v80
	v_exp_f32_e32 v187, v85
	v_add_f32_e32 v80, v169, v80
	v_exp_f32_e32 v188, v86
	v_add_f32_e32 v80, v170, v80
	v_exp_f32_e32 v189, v87
	v_add_f32_e32 v80, v171, v80
	v_add_f32_e32 v80, v186, v80
	v_add_f32_e32 v80, v187, v80
	v_add_f32_e32 v80, v188, v80
	v_add_f32_e32 v80, v189, v80
	v_add_f32_e32 v80, v190, v80
	v_add_f32_e32 v80, v191, v80
	v_add_f32_e32 v80, v192, v80
	v_add_f32_e32 v80, v193, v80
	v_add_f32_e32 v80, v241, v80
	v_add_f32_e32 v80, v242, v80
	v_add_f32_e32 v80, v94, v80
	v_add_f32_e32 v80, v95, v80
	v_mov_b32_e32 v81, v80
	v_cvt_pk_bf16_f32 v82, v172, v173
	v_cvt_pk_bf16_f32 v83, v182, v195
	v_cvt_pk_bf16_f32 v84, v196, v197
	s_nop 1
	v_permlane32_swap_b32_e32 v80, v81
	v_cvt_pk_bf16_f32 v85, v198, v199
	v_permlane32_swap_b32_e32 v82, v84
	v_cvt_pk_bf16_f32 v86, v200, v234
	v_cvt_pk_bf16_f32 v87, v235, v236
	v_cvt_pk_bf16_f32 v88, v237, v238
	v_cvt_pk_bf16_f32 v89, v239, v240
	v_cvt_pk_bf16_f32 v90, v168, v169
	v_cvt_pk_bf16_f32 v91, v170, v171
	v_cvt_pk_bf16_f32 v92, v186, v187
	v_cvt_pk_bf16_f32 v93, v188, v189
	v_cvt_pk_bf16_f32 v168, v190, v191
	v_cvt_pk_bf16_f32 v169, v192, v193
	v_cvt_pk_bf16_f32 v170, v241, v242
	v_cvt_pk_bf16_f32 v171, v94, v95
	v_lshl_add_u32 v94, s13, 14, v205
	ds_read_b64_tr_b16 v[186:187], v94 offset:0
	ds_read_b64_tr_b16 v[188:189], v94 offset:0x800
	ds_read_b64_tr_b16 v[190:191], v94 offset:0x1000
	ds_read_b64_tr_b16 v[192:193], v94 offset:0x1800
	ds_read_b64_tr_b16 v[196:197], v94 offset:0x2000
	ds_read_b64_tr_b16 v[198:199], v94 offset:0x2800
	ds_read_b64_tr_b16 v[234:235], v94 offset:0x3000
	ds_read_b64_tr_b16 v[236:237], v94 offset:0x3800
	v_permlane32_swap_b32_e32 v83, v85
	v_permlane32_swap_b32_e32 v86, v88
	v_permlane32_swap_b32_e32 v87, v89
	v_permlane32_swap_b32_e32 v90, v92
	v_permlane32_swap_b32_e32 v91, v93
	v_permlane32_swap_b32_e32 v168, v170
	v_permlane32_swap_b32_e32 v169, v171
	s_setprio 0
	s_waitcnt lgkmcnt(0)
	s_nop 0
	v_mfma_f32_32x32x16_bf16 v[0:15], v[82:85], v[186:189], v[0:15]
	ds_read_b64_tr_b16 v[186:187], v94 offset:0x200
	ds_read_b64_tr_b16 v[188:189], v94 offset:0xa00
	v_mfma_f32_32x32x16_bf16 v[0:15], v[86:89], v[190:193], v[0:15]
	ds_read_b64_tr_b16 v[190:191], v94 offset:0x1200
	ds_read_b64_tr_b16 v[192:193], v94 offset:0x1a00
	v_mfma_f32_32x32x16_bf16 v[0:15], v[90:93], v[196:199], v[0:15]
	ds_read_b64_tr_b16 v[196:197], v94 offset:0x2200
	ds_read_b64_tr_b16 v[198:199], v94 offset:0x2a00
	v_mfma_f32_32x32x16_bf16 v[0:15], v[168:171], v[234:237], v[0:15]
	ds_read_b64_tr_b16 v[234:235], v94 offset:0x3200
	ds_read_b64_tr_b16 v[236:237], v94 offset:0x3a00
	s_waitcnt lgkmcnt(0)
	v_mfma_f32_32x32x16_bf16 v[48:63], v[82:85], v[186:189], v[48:63]
	ds_read_b64_tr_b16 v[186:187], v94 offset:0x400
	ds_read_b64_tr_b16 v[188:189], v94 offset:0xc00
	v_mfma_f32_32x32x16_bf16 v[48:63], v[86:89], v[190:193], v[48:63]
	ds_read_b64_tr_b16 v[190:191], v94 offset:0x1400
	ds_read_b64_tr_b16 v[192:193], v94 offset:0x1c00
	v_mfma_f32_32x32x16_bf16 v[48:63], v[90:93], v[196:199], v[48:63]
	ds_read_b64_tr_b16 v[196:197], v94 offset:0x2400
	ds_read_b64_tr_b16 v[198:199], v94 offset:0x2c00
	v_mfma_f32_32x32x16_bf16 v[48:63], v[168:171], v[234:237], v[48:63]
	ds_read_b64_tr_b16 v[234:235], v94 offset:0x3400
	ds_read_b64_tr_b16 v[236:237], v94 offset:0x3c00
	s_waitcnt lgkmcnt(0)
	v_mfma_f32_32x32x16_bf16 v[32:47], v[82:85], v[186:189], v[32:47]
	ds_read_b64_tr_b16 v[186:187], v94 offset:0x600
	ds_read_b64_tr_b16 v[188:189], v94 offset:0xe00
	v_mfma_f32_32x32x16_bf16 v[32:47], v[86:89], v[190:193], v[32:47]
	ds_read_b64_tr_b16 v[190:191], v94 offset:0x1600
	ds_read_b64_tr_b16 v[192:193], v94 offset:0x1e00
	v_mfma_f32_32x32x16_bf16 v[32:47], v[90:93], v[196:199], v[32:47]
	ds_read_b64_tr_b16 v[196:197], v94 offset:0x2600
	ds_read_b64_tr_b16 v[198:199], v94 offset:0x2e00
	v_mfma_f32_32x32x16_bf16 v[32:47], v[168:171], v[234:237], v[32:47]
	ds_read_b64_tr_b16 v[234:235], v94 offset:0x3600
	ds_read_b64_tr_b16 v[236:237], v94 offset:0x3e00
	s_waitcnt lgkmcnt(0)
	v_mfma_f32_32x32x16_bf16 v[16:31], v[82:85], v[186:189], v[16:31]
	v_max_f32_e32 v82, v97, v97
	v_max_f32_e32 v83, v96, v96
	v_max_f32_e32 v82, v83, v82
	v_max3_f32 v82, v82, v98, v99
	v_max3_f32 v82, v82, v100, v101
	v_max3_f32 v82, v82, v102, v103
	v_max3_f32 v82, v82, v104, v105
	v_mfma_f32_32x32x16_bf16 v[16:31], v[86:89], v[190:193], v[16:31]
	v_max3_f32 v82, v82, v106, v107
	v_max3_f32 v82, v82, v108, v109
	v_max3_f32 v82, v82, v110, v111
	v_max3_f32 v82, v82, v64, v65
	v_max3_f32 v82, v82, v66, v67
	v_max3_f32 v82, v82, v68, v69
	v_max3_f32 v82, v82, v70, v71
	v_mfma_f32_32x32x16_bf16 v[16:31], v[90:93], v[196:199], v[16:31]
	v_max3_f32 v82, v82, v72, v73
	v_max3_f32 v82, v82, v74, v75
	v_max3_f32 v82, v82, v76, v77
	v_max3_f32 v82, v82, v78, v79
	v_mov_b32_e32 v83, v82
	s_nop 1
	v_permlane32_swap_b32_e32 v82, v83
	v_max_f32_e32 v83, v83, v83
	v_max_f32_e32 v82, v82, v82
	v_mfma_f32_32x32x16_bf16 v[16:31], v[168:171], v[234:237], v[16:31]
	v_max_f32_e32 v82, v82, v83
	v_sub_f32_e32 v83, v82, v184
	s_mov_b32 s0, 0x41300000
	v_cmp_ge_f32_e32 vcc, s0, v83
	v_mov_b32_e32 v182, v184
	s_cmp_eq_u64 vcc, exec
	s_cbranch_scc0 .Latt_slow2
	s_cmp_lg_u32 s19, 0
	s_cbranch_scc0 .LBB0_229
	v_mov_b32_e32 v184, 1.0
